# GEMM unit loops: accumulator zeroing with 64-bit moves (half the instructions per unit)
# speedup vs baseline: 1.0143x; 1.0143x over previous
; #define PG8_BAR __builtin_amdgcn_s_barrier()
; #define PG8_BAR __builtin_amdgcn_s_barrier()
; template <class Epi, class Sched>
; __device__ __forceinline__ void gemm_phase(LAS unsigned char* lds, const Gemm g, const Sched& S, const Epi& E) {
;     ...
;         if (!has_next) break;
; #pragma unroll
;         for (int a = 0; a < 2; ++a)
; #pragma unroll
;             for (int b = 0; b < 2; ++b)
; #pragma unroll
;                 for (int m = 0; m < 4; ++m)
; #pragma unroll
;                     for (int n = 0; n < 2; ++n) acc[a][b][m][n] = (f32x4){0.f, 0.f, 0.f, 0.f};
;         cur = nxt; cA = nA; cB = nB; ++ui;
;         if (wr == 1) PG8_BAR;
.LBB0_304:
	v_mov_b32_e32 v125, 0
	s_andn2_b64 vcc, exec, s[24:25]
	v_mov_b32_e32 v124, v125
	v_mov_b64_e32 v[122:123], 0
	v_mov_b64_e32 v[128:129], 0
	v_mov_b64_e32 v[126:127], 0
	v_mov_b64_e32 v[112:113], 0
	v_mov_b64_e32 v[110:111], 0
	v_mov_b64_e32 v[108:109], 0
	v_mov_b64_e32 v[106:107], 0
	v_mov_b64_e32 v[96:97], 0
	v_mov_b64_e32 v[94:95], 0
	v_mov_b64_e32 v[92:93], 0
	v_mov_b64_e32 v[90:91], 0
	v_mov_b64_e32 v[80:81], 0
	v_mov_b64_e32 v[78:79], 0
	v_mov_b64_e32 v[76:77], 0
	v_mov_b64_e32 v[74:75], 0
	v_mov_b64_e32 v[120:121], 0
	v_mov_b64_e32 v[118:119], 0
	v_mov_b64_e32 v[116:117], 0
	v_mov_b64_e32 v[114:115], 0
	v_mov_b64_e32 v[104:105], 0
	v_mov_b64_e32 v[102:103], 0
	v_mov_b64_e32 v[100:101], 0
	v_mov_b64_e32 v[98:99], 0
	v_mov_b64_e32 v[88:89], 0
	v_mov_b64_e32 v[86:87], 0
	v_mov_b64_e32 v[84:85], 0
	v_mov_b64_e32 v[82:83], 0
	v_mov_b64_e32 v[72:73], 0
	v_mov_b64_e32 v[70:71], 0
	v_mov_b64_e32 v[68:69], 0
	v_mov_b64_e32 v[66:67], 0
	v_mov_b64_e32 v[64:65], 0
	v_mov_b64_e32 v[62:63], 0
	v_mov_b64_e32 v[60:61], 0
	v_mov_b64_e32 v[58:59], 0
	v_mov_b64_e32 v[48:49], 0
	v_mov_b64_e32 v[46:47], 0
	v_mov_b64_e32 v[44:45], 0
	v_mov_b64_e32 v[42:43], 0
	v_mov_b64_e32 v[32:33], 0
	v_mov_b64_e32 v[30:31], 0
	v_mov_b64_e32 v[28:29], 0
	v_mov_b64_e32 v[26:27], 0
	v_mov_b64_e32 v[16:17], 0
	v_mov_b64_e32 v[14:15], 0
	v_mov_b64_e32 v[12:13], 0
	v_mov_b64_e32 v[10:11], 0
	v_mov_b64_e32 v[56:57], 0
	v_mov_b64_e32 v[54:55], 0
	v_mov_b64_e32 v[52:53], 0
	v_mov_b64_e32 v[50:51], 0
	v_mov_b64_e32 v[40:41], 0
	v_mov_b64_e32 v[38:39], 0
	v_mov_b64_e32 v[36:37], 0
	v_mov_b64_e32 v[34:35], 0
	v_mov_b64_e32 v[24:25], 0
	v_mov_b64_e32 v[22:23], 0
	v_mov_b64_e32 v[20:21], 0
	v_mov_b64_e32 v[18:19], 0
	v_mov_b64_e32 v[8:9], 0
	v_mov_b64_e32 v[6:7], 0
	v_mov_b64_e32 v[4:5], 0
	v_mov_b64_e32 v[2:3], 0
	s_cbranch_vccnz .LBB0_314
	s_add_u32 s38, s38, 0x80
	s_addc_u32 s39, s39, 0
	s_add_u32 s59, s40, 0x100
	v_mov_b32_e32 v2, 0
	s_addc_u32 s60, s41, 0
	s_mov_b32 s40, 0
	v_mov_b32_e32 v3, v2
	v_mov_b64_e32 v[4:5], 0
	v_mov_b64_e32 v[6:7], 0
	v_mov_b64_e32 v[8:9], 0
	v_mov_b64_e32 v[18:19], 0
	v_mov_b64_e32 v[20:21], 0
	v_mov_b64_e32 v[22:23], 0
	v_mov_b64_e32 v[24:25], 0
	v_mov_b64_e32 v[34:35], 0
	v_mov_b64_e32 v[36:37], 0
	v_mov_b64_e32 v[38:39], 0
	v_mov_b64_e32 v[40:41], 0
	v_mov_b64_e32 v[50:51], 0
	v_mov_b64_e32 v[52:53], 0
	v_mov_b64_e32 v[54:55], 0
	v_mov_b64_e32 v[56:57], 0
	v_mov_b64_e32 v[10:11], 0
	v_mov_b64_e32 v[12:13], 0
	v_mov_b64_e32 v[14:15], 0
	v_mov_b64_e32 v[16:17], 0
	v_mov_b64_e32 v[26:27], 0
	v_mov_b64_e32 v[28:29], 0
	v_mov_b64_e32 v[30:31], 0
	v_mov_b64_e32 v[32:33], 0
	v_mov_b64_e32 v[42:43], 0
	v_mov_b64_e32 v[44:45], 0
	v_mov_b64_e32 v[46:47], 0
	v_mov_b64_e32 v[48:49], 0
	v_mov_b64_e32 v[58:59], 0
	v_mov_b64_e32 v[60:61], 0
	v_mov_b64_e32 v[62:63], 0
	v_mov_b64_e32 v[64:65], 0
	v_mov_b64_e32 v[66:67], 0
	v_mov_b64_e32 v[68:69], 0
	v_mov_b64_e32 v[70:71], 0
	v_mov_b64_e32 v[72:73], 0
	v_mov_b64_e32 v[82:83], 0
	v_mov_b64_e32 v[84:85], 0
	v_mov_b64_e32 v[86:87], 0
	v_mov_b64_e32 v[88:89], 0
	v_mov_b64_e32 v[98:99], 0
	v_mov_b64_e32 v[100:101], 0
	v_mov_b64_e32 v[102:103], 0
	v_mov_b64_e32 v[104:105], 0
	v_mov_b64_e32 v[114:115], 0
	v_mov_b64_e32 v[116:117], 0
	v_mov_b64_e32 v[118:119], 0
	v_mov_b64_e32 v[120:121], 0
	v_mov_b64_e32 v[74:75], 0
	v_mov_b64_e32 v[76:77], 0
	v_mov_b64_e32 v[78:79], 0
	v_mov_b64_e32 v[80:81], 0
	v_mov_b64_e32 v[90:91], 0
	v_mov_b64_e32 v[92:93], 0
	v_mov_b64_e32 v[94:95], 0
	v_mov_b64_e32 v[96:97], 0
	v_mov_b64_e32 v[106:107], 0
	v_mov_b64_e32 v[108:109], 0
	v_mov_b64_e32 v[110:111], 0
	v_mov_b64_e32 v[112:113], 0
	v_mov_b64_e32 v[126:127], 0
	v_mov_b64_e32 v[128:129], 0
	v_mov_b64_e32 v[122:123], 0
	v_mov_b64_e32 v[124:125], 0

; #define PG8_BAR __builtin_amdgcn_s_barrier()
; #define PG8_BAR __builtin_amdgcn_s_barrier()
; template <class Epi, class Sched>
; __device__ __forceinline__ void gemm_phase(LAS unsigned char* lds, const Gemm g, const Sched& S, const Epi& E) {
;     ...
;         if (!has_next) break;
; #pragma unroll
;         for (int a = 0; a < 2; ++a)
; #pragma unroll
;             for (int b = 0; b < 2; ++b)
; #pragma unroll
;                 for (int m = 0; m < 4; ++m)
; #pragma unroll
;                     for (int n = 0; n < 2; ++n) acc[a][b][m][n] = (f32x4){0.f, 0.f, 0.f, 0.f};
;         cur = nxt; cA = nA; cB = nB; ++ui;
;         if (wr == 1) PG8_BAR;
.LBB0_645:
	v_mov_b32_e32 v125, 0
	s_andn2_b64 vcc, exec, s[22:23]
	v_mov_b32_e32 v124, v125
	v_mov_b64_e32 v[122:123], 0
	v_mov_b64_e32 v[128:129], 0
	v_mov_b64_e32 v[126:127], 0
	v_mov_b64_e32 v[112:113], 0
	v_mov_b64_e32 v[110:111], 0
	v_mov_b64_e32 v[108:109], 0
	v_mov_b64_e32 v[106:107], 0
	v_mov_b64_e32 v[96:97], 0
	v_mov_b64_e32 v[94:95], 0
	v_mov_b64_e32 v[92:93], 0
	v_mov_b64_e32 v[90:91], 0
	v_mov_b64_e32 v[80:81], 0
	v_mov_b64_e32 v[78:79], 0
	v_mov_b64_e32 v[76:77], 0
	v_mov_b64_e32 v[74:75], 0
	v_mov_b64_e32 v[120:121], 0
	v_mov_b64_e32 v[118:119], 0
	v_mov_b64_e32 v[116:117], 0
	v_mov_b64_e32 v[114:115], 0
	v_mov_b64_e32 v[104:105], 0
	v_mov_b64_e32 v[102:103], 0
	v_mov_b64_e32 v[100:101], 0
	v_mov_b64_e32 v[98:99], 0
	v_mov_b64_e32 v[88:89], 0
	v_mov_b64_e32 v[86:87], 0
	v_mov_b64_e32 v[84:85], 0
	v_mov_b64_e32 v[82:83], 0
	v_mov_b64_e32 v[72:73], 0
	v_mov_b64_e32 v[70:71], 0
	v_mov_b64_e32 v[68:69], 0
	v_mov_b64_e32 v[66:67], 0
	v_mov_b64_e32 v[64:65], 0
	v_mov_b64_e32 v[62:63], 0
	v_mov_b64_e32 v[60:61], 0
	v_mov_b64_e32 v[58:59], 0
	v_mov_b64_e32 v[48:49], 0
	v_mov_b64_e32 v[46:47], 0
	v_mov_b64_e32 v[44:45], 0
	v_mov_b64_e32 v[42:43], 0
	v_mov_b64_e32 v[32:33], 0
	v_mov_b64_e32 v[30:31], 0
	v_mov_b64_e32 v[28:29], 0
	v_mov_b64_e32 v[26:27], 0
	v_mov_b64_e32 v[16:17], 0
	v_mov_b64_e32 v[14:15], 0
	v_mov_b64_e32 v[12:13], 0
	v_mov_b64_e32 v[10:11], 0
	v_mov_b64_e32 v[56:57], 0
	v_mov_b64_e32 v[54:55], 0
	v_mov_b64_e32 v[52:53], 0
	v_mov_b64_e32 v[50:51], 0
	v_mov_b64_e32 v[40:41], 0
	v_mov_b64_e32 v[38:39], 0
	v_mov_b64_e32 v[36:37], 0
	v_mov_b64_e32 v[34:35], 0
	v_mov_b64_e32 v[24:25], 0
	v_mov_b64_e32 v[22:23], 0
	v_mov_b64_e32 v[20:21], 0
	v_mov_b64_e32 v[18:19], 0
	v_mov_b64_e32 v[8:9], 0
	v_mov_b64_e32 v[6:7], 0
	v_mov_b64_e32 v[4:5], 0
	v_mov_b64_e32 v[2:3], 0
	s_cbranch_vccnz .LBB0_648
	s_add_u32 s6, s40, 0x80
	s_addc_u32 s7, s41, 0
	s_add_u32 s40, s38, 0x100
	v_mov_b32_e32 v2, 0
	s_addc_u32 s41, s39, 0
	s_mov_b32 s38, 0
	v_mov_b32_e32 v3, v2
	v_mov_b64_e32 v[4:5], 0
	v_mov_b64_e32 v[6:7], 0
	v_mov_b64_e32 v[8:9], 0
	v_mov_b64_e32 v[18:19], 0
	v_mov_b64_e32 v[20:21], 0
	v_mov_b64_e32 v[22:23], 0
	v_mov_b64_e32 v[24:25], 0
	v_mov_b64_e32 v[34:35], 0
	v_mov_b64_e32 v[36:37], 0
	v_mov_b64_e32 v[38:39], 0
	v_mov_b64_e32 v[40:41], 0
	v_mov_b64_e32 v[50:51], 0
	v_mov_b64_e32 v[52:53], 0
	v_mov_b64_e32 v[54:55], 0
	v_mov_b64_e32 v[56:57], 0
	v_mov_b64_e32 v[10:11], 0
	v_mov_b64_e32 v[12:13], 0
	v_mov_b64_e32 v[14:15], 0
	v_mov_b64_e32 v[16:17], 0
	v_mov_b64_e32 v[26:27], 0
	v_mov_b64_e32 v[28:29], 0
	v_mov_b64_e32 v[30:31], 0
	v_mov_b64_e32 v[32:33], 0
	v_mov_b64_e32 v[42:43], 0
	v_mov_b64_e32 v[44:45], 0
	v_mov_b64_e32 v[46:47], 0
	v_mov_b64_e32 v[48:49], 0
	v_mov_b64_e32 v[58:59], 0
	v_mov_b64_e32 v[60:61], 0
	v_mov_b64_e32 v[62:63], 0
	v_mov_b64_e32 v[64:65], 0
	v_mov_b64_e32 v[66:67], 0
	v_mov_b64_e32 v[68:69], 0
	v_mov_b64_e32 v[70:71], 0
	v_mov_b64_e32 v[72:73], 0
	v_mov_b64_e32 v[82:83], 0
	v_mov_b64_e32 v[84:85], 0
	v_mov_b64_e32 v[86:87], 0
	v_mov_b64_e32 v[88:89], 0
	v_mov_b64_e32 v[98:99], 0
	v_mov_b64_e32 v[100:101], 0
	v_mov_b64_e32 v[102:103], 0
	v_mov_b64_e32 v[104:105], 0
	v_mov_b64_e32 v[114:115], 0
	v_mov_b64_e32 v[116:117], 0
	v_mov_b64_e32 v[118:119], 0
	v_mov_b64_e32 v[120:121], 0
	v_mov_b64_e32 v[74:75], 0
	v_mov_b64_e32 v[76:77], 0
	v_mov_b64_e32 v[78:79], 0
	v_mov_b64_e32 v[80:81], 0
	v_mov_b64_e32 v[90:91], 0
	v_mov_b64_e32 v[92:93], 0
	v_mov_b64_e32 v[94:95], 0
	v_mov_b64_e32 v[96:97], 0
	v_mov_b64_e32 v[106:107], 0
	v_mov_b64_e32 v[108:109], 0
	v_mov_b64_e32 v[110:111], 0
	v_mov_b64_e32 v[112:113], 0
	v_mov_b64_e32 v[126:127], 0
	v_mov_b64_e32 v[128:129], 0
	v_mov_b64_e32 v[122:123], 0
	v_mov_b64_e32 v[124:125], 0

; #define PG8_BAR __builtin_amdgcn_s_barrier()
; #define PG8_BAR __builtin_amdgcn_s_barrier()
; template <class Epi, class Sched>
; __device__ __forceinline__ void gemm_phase(LAS unsigned char* lds, const Gemm g, const Sched& S, const Epi& E) {
;     ...
;         if (!has_next) break;
; #pragma unroll
;         for (int a = 0; a < 2; ++a)
; #pragma unroll
;             for (int b = 0; b < 2; ++b)
; #pragma unroll
;                 for (int m = 0; m < 4; ++m)
; #pragma unroll
;                     for (int n = 0; n < 2; ++n) acc[a][b][m][n] = (f32x4){0.f, 0.f, 0.f, 0.f};
;         cur = nxt; cA = nA; cB = nB; ++ui;
;         if (wr == 1) PG8_BAR;
.LBB0_736:
	v_mov_b32_e32 v125, 0
	s_andn2_b64 vcc, exec, s[22:23]
	v_mov_b32_e32 v124, v125
	v_mov_b64_e32 v[122:123], 0
	v_mov_b64_e32 v[128:129], 0
	v_mov_b64_e32 v[126:127], 0
	v_mov_b64_e32 v[112:113], 0
	v_mov_b64_e32 v[110:111], 0
	v_mov_b64_e32 v[108:109], 0
	v_mov_b64_e32 v[106:107], 0
	v_mov_b64_e32 v[96:97], 0
	v_mov_b64_e32 v[94:95], 0
	v_mov_b64_e32 v[92:93], 0
	v_mov_b64_e32 v[90:91], 0
	v_mov_b64_e32 v[80:81], 0
	v_mov_b64_e32 v[78:79], 0
	v_mov_b64_e32 v[76:77], 0
	v_mov_b64_e32 v[74:75], 0
	v_mov_b64_e32 v[120:121], 0
	v_mov_b64_e32 v[118:119], 0
	v_mov_b64_e32 v[116:117], 0
	v_mov_b64_e32 v[114:115], 0
	v_mov_b64_e32 v[104:105], 0
	v_mov_b64_e32 v[102:103], 0
	v_mov_b64_e32 v[100:101], 0
	v_mov_b64_e32 v[98:99], 0
	v_mov_b64_e32 v[88:89], 0
	v_mov_b64_e32 v[86:87], 0
	v_mov_b64_e32 v[84:85], 0
	v_mov_b64_e32 v[82:83], 0
	v_mov_b64_e32 v[72:73], 0
	v_mov_b64_e32 v[70:71], 0
	v_mov_b64_e32 v[68:69], 0
	v_mov_b64_e32 v[66:67], 0
	v_mov_b64_e32 v[64:65], 0
	v_mov_b64_e32 v[62:63], 0
	v_mov_b64_e32 v[60:61], 0
	v_mov_b64_e32 v[58:59], 0
	v_mov_b64_e32 v[48:49], 0
	v_mov_b64_e32 v[46:47], 0
	v_mov_b64_e32 v[44:45], 0
	v_mov_b64_e32 v[42:43], 0
	v_mov_b64_e32 v[32:33], 0
	v_mov_b64_e32 v[30:31], 0
	v_mov_b64_e32 v[28:29], 0
	v_mov_b64_e32 v[26:27], 0
	v_mov_b64_e32 v[16:17], 0
	v_mov_b64_e32 v[14:15], 0
	v_mov_b64_e32 v[12:13], 0
	v_mov_b64_e32 v[10:11], 0
	v_mov_b64_e32 v[56:57], 0
	v_mov_b64_e32 v[54:55], 0
	v_mov_b64_e32 v[52:53], 0
	v_mov_b64_e32 v[50:51], 0
	v_mov_b64_e32 v[40:41], 0
	v_mov_b64_e32 v[38:39], 0
	v_mov_b64_e32 v[36:37], 0
	v_mov_b64_e32 v[34:35], 0
	v_mov_b64_e32 v[24:25], 0
	v_mov_b64_e32 v[22:23], 0
	v_mov_b64_e32 v[20:21], 0
	v_mov_b64_e32 v[18:19], 0
	v_mov_b64_e32 v[8:9], 0
	v_mov_b64_e32 v[6:7], 0
	v_mov_b64_e32 v[4:5], 0
	v_mov_b64_e32 v[2:3], 0
	s_cbranch_vccnz .LBB0_739
	s_add_u32 s28, s28, 0x80
	s_addc_u32 s29, s29, 0
	s_add_u32 s58, s38, 0x100
	v_mov_b32_e32 v2, 0
	s_addc_u32 s59, s39, 0
	s_mov_b32 s38, 0
	v_mov_b32_e32 v3, v2
	v_mov_b64_e32 v[4:5], 0
	v_mov_b64_e32 v[6:7], 0
	v_mov_b64_e32 v[8:9], 0
	v_mov_b64_e32 v[18:19], 0
	v_mov_b64_e32 v[20:21], 0
	v_mov_b64_e32 v[22:23], 0
	v_mov_b64_e32 v[24:25], 0
	v_mov_b64_e32 v[34:35], 0
	v_mov_b64_e32 v[36:37], 0
	v_mov_b64_e32 v[38:39], 0
	v_mov_b64_e32 v[40:41], 0
	v_mov_b64_e32 v[50:51], 0
	v_mov_b64_e32 v[52:53], 0
	v_mov_b64_e32 v[54:55], 0
	v_mov_b64_e32 v[56:57], 0
	v_mov_b64_e32 v[10:11], 0
	v_mov_b64_e32 v[12:13], 0
	v_mov_b64_e32 v[14:15], 0
	v_mov_b64_e32 v[16:17], 0
	v_mov_b64_e32 v[26:27], 0
	v_mov_b64_e32 v[28:29], 0
	v_mov_b64_e32 v[30:31], 0
	v_mov_b64_e32 v[32:33], 0
	v_mov_b64_e32 v[42:43], 0
	v_mov_b64_e32 v[44:45], 0
	v_mov_b64_e32 v[46:47], 0
	v_mov_b64_e32 v[48:49], 0
	v_mov_b64_e32 v[58:59], 0
	v_mov_b64_e32 v[60:61], 0
	v_mov_b64_e32 v[62:63], 0
	v_mov_b64_e32 v[64:65], 0
	v_mov_b64_e32 v[66:67], 0
	v_mov_b64_e32 v[68:69], 0
	v_mov_b64_e32 v[70:71], 0
	v_mov_b64_e32 v[72:73], 0
	v_mov_b64_e32 v[82:83], 0
	v_mov_b64_e32 v[84:85], 0
	v_mov_b64_e32 v[86:87], 0
	v_mov_b64_e32 v[88:89], 0
	v_mov_b64_e32 v[98:99], 0
	v_mov_b64_e32 v[100:101], 0
	v_mov_b64_e32 v[102:103], 0
	v_mov_b64_e32 v[104:105], 0
	v_mov_b64_e32 v[114:115], 0
	v_mov_b64_e32 v[116:117], 0
	v_mov_b64_e32 v[118:119], 0
	v_mov_b64_e32 v[120:121], 0
	v_mov_b64_e32 v[74:75], 0
	v_mov_b64_e32 v[76:77], 0
	v_mov_b64_e32 v[78:79], 0
	v_mov_b64_e32 v[80:81], 0
	v_mov_b64_e32 v[90:91], 0
	v_mov_b64_e32 v[92:93], 0
	v_mov_b64_e32 v[94:95], 0
	v_mov_b64_e32 v[96:97], 0
	v_mov_b64_e32 v[106:107], 0
	v_mov_b64_e32 v[108:109], 0
	v_mov_b64_e32 v[110:111], 0
	v_mov_b64_e32 v[112:113], 0
	v_mov_b64_e32 v[126:127], 0
	v_mov_b64_e32 v[128:129], 0
	v_mov_b64_e32 v[122:123], 0
	v_mov_b64_e32 v[124:125], 0

; #define PG8_BAR __builtin_amdgcn_s_barrier()
; #define PG8_BAR __builtin_amdgcn_s_barrier()
; template <class Epi, class Sched>
; __device__ __forceinline__ void gemm_phase(LAS unsigned char* lds, const Gemm g, const Sched& S, const Epi& E) {
;     ...
;         if (!has_next) break;
; #pragma unroll
;         for (int a = 0; a < 2; ++a)
; #pragma unroll
;             for (int b = 0; b < 2; ++b)
; #pragma unroll
;                 for (int m = 0; m < 4; ++m)
; #pragma unroll
;                     for (int n = 0; n < 2; ++n) acc[a][b][m][n] = (f32x4){0.f, 0.f, 0.f, 0.f};
;         cur = nxt; cA = nA; cB = nB; ++ui;
;         if (wr == 1) PG8_BAR;
.LBB0_762:
	v_mov_b32_e32 v125, 0
	s_andn2_b64 vcc, exec, s[22:23]
	v_mov_b32_e32 v124, v125
	v_mov_b64_e32 v[122:123], 0
	v_mov_b64_e32 v[128:129], 0
	v_mov_b64_e32 v[126:127], 0
	v_mov_b64_e32 v[112:113], 0
	v_mov_b64_e32 v[110:111], 0
	v_mov_b64_e32 v[108:109], 0
	v_mov_b64_e32 v[106:107], 0
	v_mov_b64_e32 v[96:97], 0
	v_mov_b64_e32 v[94:95], 0
	v_mov_b64_e32 v[92:93], 0
	v_mov_b64_e32 v[90:91], 0
	v_mov_b64_e32 v[80:81], 0
	v_mov_b64_e32 v[78:79], 0
	v_mov_b64_e32 v[76:77], 0
	v_mov_b64_e32 v[74:75], 0
	v_mov_b64_e32 v[120:121], 0
	v_mov_b64_e32 v[118:119], 0
	v_mov_b64_e32 v[116:117], 0
	v_mov_b64_e32 v[114:115], 0
	v_mov_b64_e32 v[104:105], 0
	v_mov_b64_e32 v[102:103], 0
	v_mov_b64_e32 v[100:101], 0
	v_mov_b64_e32 v[98:99], 0
	v_mov_b64_e32 v[88:89], 0
	v_mov_b64_e32 v[86:87], 0
	v_mov_b64_e32 v[84:85], 0
	v_mov_b64_e32 v[82:83], 0
	v_mov_b64_e32 v[72:73], 0
	v_mov_b64_e32 v[70:71], 0
	v_mov_b64_e32 v[68:69], 0
	v_mov_b64_e32 v[66:67], 0
	v_mov_b64_e32 v[64:65], 0
	v_mov_b64_e32 v[62:63], 0
	v_mov_b64_e32 v[60:61], 0
	v_mov_b64_e32 v[58:59], 0
	v_mov_b64_e32 v[48:49], 0
	v_mov_b64_e32 v[46:47], 0
	v_mov_b64_e32 v[44:45], 0
	v_mov_b64_e32 v[42:43], 0
	v_mov_b64_e32 v[32:33], 0
	v_mov_b64_e32 v[30:31], 0
	v_mov_b64_e32 v[28:29], 0
	v_mov_b64_e32 v[26:27], 0
	v_mov_b64_e32 v[16:17], 0
	v_mov_b64_e32 v[14:15], 0
	v_mov_b64_e32 v[12:13], 0
	v_mov_b64_e32 v[10:11], 0
	v_mov_b64_e32 v[56:57], 0
	v_mov_b64_e32 v[54:55], 0
	v_mov_b64_e32 v[52:53], 0
	v_mov_b64_e32 v[50:51], 0
	v_mov_b64_e32 v[40:41], 0
	v_mov_b64_e32 v[38:39], 0
	v_mov_b64_e32 v[36:37], 0
	v_mov_b64_e32 v[34:35], 0
	v_mov_b64_e32 v[24:25], 0
	v_mov_b64_e32 v[22:23], 0
	v_mov_b64_e32 v[20:21], 0
	v_mov_b64_e32 v[18:19], 0
	v_mov_b64_e32 v[8:9], 0
	v_mov_b64_e32 v[6:7], 0
	v_mov_b64_e32 v[4:5], 0
	v_mov_b64_e32 v[2:3], 0
	s_cbranch_vccnz .LBB0_766
	s_add_u32 s38, s38, 0x80
	s_addc_u32 s39, s39, 0
	s_add_u32 s27, s40, 0x100
	v_mov_b32_e32 v2, 0
	s_addc_u32 s55, s41, 0
	s_mov_b32 s40, 0
	v_mov_b32_e32 v3, v2
	v_mov_b64_e32 v[4:5], 0
	v_mov_b64_e32 v[6:7], 0
	v_mov_b64_e32 v[8:9], 0
	v_mov_b64_e32 v[18:19], 0
	v_mov_b64_e32 v[20:21], 0
	v_mov_b64_e32 v[22:23], 0
	v_mov_b64_e32 v[24:25], 0
	v_mov_b64_e32 v[34:35], 0
	v_mov_b64_e32 v[36:37], 0
	v_mov_b64_e32 v[38:39], 0
	v_mov_b64_e32 v[40:41], 0
	v_mov_b64_e32 v[50:51], 0
	v_mov_b64_e32 v[52:53], 0
	v_mov_b64_e32 v[54:55], 0
	v_mov_b64_e32 v[56:57], 0
	v_mov_b64_e32 v[10:11], 0
	v_mov_b64_e32 v[12:13], 0
	v_mov_b64_e32 v[14:15], 0
	v_mov_b64_e32 v[16:17], 0
	v_mov_b64_e32 v[26:27], 0
	v_mov_b64_e32 v[28:29], 0
	v_mov_b64_e32 v[30:31], 0
	v_mov_b64_e32 v[32:33], 0
	v_mov_b64_e32 v[42:43], 0
	v_mov_b64_e32 v[44:45], 0
	v_mov_b64_e32 v[46:47], 0
	v_mov_b64_e32 v[48:49], 0
	v_mov_b64_e32 v[58:59], 0
	v_mov_b64_e32 v[60:61], 0
	v_mov_b64_e32 v[62:63], 0
	v_mov_b64_e32 v[64:65], 0
	v_mov_b64_e32 v[66:67], 0
	v_mov_b64_e32 v[68:69], 0
	v_mov_b64_e32 v[70:71], 0
	v_mov_b64_e32 v[72:73], 0
	v_mov_b64_e32 v[82:83], 0
	v_mov_b64_e32 v[84:85], 0
	v_mov_b64_e32 v[86:87], 0
	v_mov_b64_e32 v[88:89], 0
	v_mov_b64_e32 v[98:99], 0
	v_mov_b64_e32 v[100:101], 0
	v_mov_b64_e32 v[102:103], 0
	v_mov_b64_e32 v[104:105], 0
	v_mov_b64_e32 v[114:115], 0
	v_mov_b64_e32 v[116:117], 0
	v_mov_b64_e32 v[118:119], 0
	v_mov_b64_e32 v[120:121], 0
	v_mov_b64_e32 v[74:75], 0
	v_mov_b64_e32 v[76:77], 0
	v_mov_b64_e32 v[78:79], 0
	v_mov_b64_e32 v[80:81], 0
	v_mov_b64_e32 v[90:91], 0
	v_mov_b64_e32 v[92:93], 0
	v_mov_b64_e32 v[94:95], 0
	v_mov_b64_e32 v[96:97], 0
	v_mov_b64_e32 v[106:107], 0
	v_mov_b64_e32 v[108:109], 0
	v_mov_b64_e32 v[110:111], 0
	v_mov_b64_e32 v[112:113], 0
	v_mov_b64_e32 v[126:127], 0
	v_mov_b64_e32 v[128:129], 0
	v_mov_b64_e32 v[122:123], 0
	v_mov_b64_e32 v[124:125], 0

; #define PG8_BAR __builtin_amdgcn_s_barrier()
; #define PG8_BAR __builtin_amdgcn_s_barrier()
; template <class Epi, class Sched>
; __device__ __forceinline__ void gemm_phase(LAS unsigned char* lds, const Gemm g, const Sched& S, const Epi& E) {
;     ...
;         if (!has_next) break;
; #pragma unroll
;         for (int a = 0; a < 2; ++a)
; #pragma unroll
;             for (int b = 0; b < 2; ++b)
; #pragma unroll
;                 for (int m = 0; m < 4; ++m)
; #pragma unroll
;                     for (int n = 0; n < 2; ++n) acc[a][b][m][n] = (f32x4){0.f, 0.f, 0.f, 0.f};
;         cur = nxt; cA = nA; cB = nB; ++ui;
;         if (wr == 1) PG8_BAR;
.LBB0_788:
	v_mov_b32_e32 v137, 0
	s_andn2_b64 vcc, exec, s[28:29]
	v_mov_b32_e32 v136, v137
	v_mov_b64_e32 v[134:135], 0
	v_mov_b64_e32 v[64:65], 0
	v_mov_b64_e32 v[62:63], 0
	v_mov_b64_e32 v[128:129], 0
	v_mov_b64_e32 v[126:127], 0
	v_mov_b64_e32 v[56:57], 0
	v_mov_b64_e32 v[54:55], 0
	v_mov_b64_e32 v[120:121], 0
	v_mov_b64_e32 v[118:119], 0
	v_mov_b64_e32 v[48:49], 0
	v_mov_b64_e32 v[46:47], 0
	v_mov_b64_e32 v[112:113], 0
	v_mov_b64_e32 v[110:111], 0
	v_mov_b64_e32 v[40:41], 0
	v_mov_b64_e32 v[38:39], 0
	v_mov_b64_e32 v[132:133], 0
	v_mov_b64_e32 v[130:131], 0
	v_mov_b64_e32 v[60:61], 0
	v_mov_b64_e32 v[58:59], 0
	v_mov_b64_e32 v[124:125], 0
	v_mov_b64_e32 v[122:123], 0
	v_mov_b64_e32 v[52:53], 0
	v_mov_b64_e32 v[50:51], 0
	v_mov_b64_e32 v[116:117], 0
	v_mov_b64_e32 v[114:115], 0
	v_mov_b64_e32 v[44:45], 0
	v_mov_b64_e32 v[42:43], 0
	v_mov_b64_e32 v[108:109], 0
	v_mov_b64_e32 v[106:107], 0
	v_mov_b64_e32 v[36:37], 0
	v_mov_b64_e32 v[34:35], 0
	v_mov_b64_e32 v[100:101], 0
	v_mov_b64_e32 v[98:99], 0
	v_mov_b64_e32 v[32:33], 0
	v_mov_b64_e32 v[30:31], 0
	v_mov_b64_e32 v[88:89], 0
	v_mov_b64_e32 v[86:87], 0
	v_mov_b64_e32 v[24:25], 0
	v_mov_b64_e32 v[22:23], 0
	v_mov_b64_e32 v[80:81], 0
	v_mov_b64_e32 v[78:79], 0
	v_mov_b64_e32 v[16:17], 0
	v_mov_b64_e32 v[14:15], 0
	v_mov_b64_e32 v[72:73], 0
	v_mov_b64_e32 v[70:71], 0
	v_mov_b64_e32 v[8:9], 0
	v_mov_b64_e32 v[6:7], 0
	v_mov_b64_e32 v[96:97], 0
	v_mov_b64_e32 v[94:95], 0
	v_mov_b64_e32 v[28:29], 0
	v_mov_b64_e32 v[26:27], 0
	v_mov_b64_e32 v[84:85], 0
	v_mov_b64_e32 v[82:83], 0
	v_mov_b64_e32 v[20:21], 0
	v_mov_b64_e32 v[18:19], 0
	v_mov_b64_e32 v[76:77], 0
	v_mov_b64_e32 v[74:75], 0
	v_mov_b64_e32 v[12:13], 0
	v_mov_b64_e32 v[10:11], 0
	v_mov_b64_e32 v[68:69], 0
	v_mov_b64_e32 v[66:67], 0
	v_mov_b64_e32 v[4:5], 0
	v_mov_b64_e32 v[2:3], 0
	s_cbranch_vccnz .LBB0_791
	s_add_u32 s0, s0, 0x80
	s_addc_u32 s1, s1, 0
	s_add_u32 s38, s38, 0x100
	v_mov_b32_e32 v2, 0
	s_addc_u32 s39, s39, 0
	s_mov_b32 s6, 0
	v_mov_b32_e32 v3, v2
	v_mov_b64_e32 v[4:5], 0
	v_mov_b64_e32 v[66:67], 0
	v_mov_b64_e32 v[68:69], 0
	v_mov_b64_e32 v[10:11], 0
	v_mov_b64_e32 v[12:13], 0
	v_mov_b64_e32 v[74:75], 0
	v_mov_b64_e32 v[76:77], 0
	v_mov_b64_e32 v[18:19], 0
	v_mov_b64_e32 v[20:21], 0
	v_mov_b64_e32 v[82:83], 0
	v_mov_b64_e32 v[84:85], 0
	v_mov_b64_e32 v[26:27], 0
	v_mov_b64_e32 v[28:29], 0
	v_mov_b64_e32 v[94:95], 0
	v_mov_b64_e32 v[96:97], 0
	v_mov_b64_e32 v[6:7], 0
	v_mov_b64_e32 v[8:9], 0
	v_mov_b64_e32 v[70:71], 0
	v_mov_b64_e32 v[72:73], 0
	v_mov_b64_e32 v[14:15], 0
	v_mov_b64_e32 v[16:17], 0
	v_mov_b64_e32 v[78:79], 0
	v_mov_b64_e32 v[80:81], 0
	v_mov_b64_e32 v[22:23], 0
	v_mov_b64_e32 v[24:25], 0
	v_mov_b64_e32 v[86:87], 0
	v_mov_b64_e32 v[88:89], 0
	v_mov_b64_e32 v[30:31], 0
	v_mov_b64_e32 v[32:33], 0
	v_mov_b64_e32 v[98:99], 0
	v_mov_b64_e32 v[100:101], 0
	v_mov_b64_e32 v[34:35], 0
	v_mov_b64_e32 v[36:37], 0
	v_mov_b64_e32 v[106:107], 0
	v_mov_b64_e32 v[108:109], 0
	v_mov_b64_e32 v[42:43], 0
	v_mov_b64_e32 v[44:45], 0
	v_mov_b64_e32 v[114:115], 0
	v_mov_b64_e32 v[116:117], 0
	v_mov_b64_e32 v[50:51], 0
	v_mov_b64_e32 v[52:53], 0
	v_mov_b64_e32 v[122:123], 0
	v_mov_b64_e32 v[124:125], 0
	v_mov_b64_e32 v[58:59], 0
	v_mov_b64_e32 v[60:61], 0
	v_mov_b64_e32 v[130:131], 0
	v_mov_b64_e32 v[132:133], 0
	v_mov_b64_e32 v[38:39], 0
	v_mov_b64_e32 v[40:41], 0
	v_mov_b64_e32 v[110:111], 0
	v_mov_b64_e32 v[112:113], 0
	v_mov_b64_e32 v[46:47], 0
	v_mov_b64_e32 v[48:49], 0
	v_mov_b64_e32 v[118:119], 0
	v_mov_b64_e32 v[120:121], 0
	v_mov_b64_e32 v[54:55], 0
	v_mov_b64_e32 v[56:57], 0
	v_mov_b64_e32 v[126:127], 0
	v_mov_b64_e32 v[128:129], 0
	v_mov_b64_e32 v[62:63], 0
	v_mov_b64_e32 v[64:65], 0
	v_mov_b64_e32 v[134:135], 0
	v_mov_b64_e32 v[136:137], 0

; template <class Epi>
; __device__ __forceinline__ void gemm_merge_fused(LAS unsigned char* lds, const bf16_t* Yb, const bf16_t* XBb, const bf16_t* WBR, const bf16_t* WG, const MergeOrder& S, const Epi& E) {
;     ...
;         const int nt = ck ? nt1 : nt0;
;         for (int t = 0; t < nt; t += 2) {
;             const bool last = (t == nt - 2);
;             const int kx = last ? nk : ck;
;             const unsigned la1 = MF_LA(ck), lax = MF_LA(kx), lbx = MF_LB(kx);
;             unsigned voffA1[2] = {Ra0 * la1 + C2, Ra0 * la1 + C2 + 64u * la1};
;             unsigned voffA[2] = {Ra0 * lax + C2, Ra0 * lax + C2 + 64u * lax};
;             unsigned voffB[2] = {Rb0 * lbx + C2, Rb0 * lbx + C2 + 64u * lbx};
;             const size_t hsA1 = (size_t)128 * la1, hsA = (size_t)128 * lax, hsB = (size_t)128 * lbx;
;             const char* a1 = cA + (size_t)(t + 1) * kstep;
;             const char* a2 = last ? nA : cA + (size_t)(t + 2) * kstep; const char* b2 = last ? nB : cB + (size_t)(t + 2) * kstep;
;             const char* a3 = a2 + kstep; const char* b3 = b2 + kstep;
;     ...
; #pragma unroll
;         for (int a = 0; a < 2; ++a)
; #pragma unroll
;             for (int b = 0; b < 2; ++b)
; #pragma unroll
;                 for (int m = 0; m < 4; ++m)
; #pragma unroll
;                     for (int n = 0; n < 2; ++n) acc[a][b][m][n] = (f32x4){0.f, 0.f, 0.f, 0.f};
.LBB0_1329:
	s_cmp_eq_u32 s69, 0
	s_cselect_b64 s[6:7], -1, 0
	s_and_b64 s[8:9], s[6:7], exec
	s_cselect_b32 s21, s49, s48
	s_cmp_lt_i32 s21, 1
	s_cbranch_scc1 .LBB0_1388
	s_add_i32 s23, s21, -2
	s_and_b64 s[6:7], s[6:7], exec
	s_cselect_b32 s36, s12, s46
	s_lshl_b64 s[8:9], s[36:37], 7
	s_add_u32 s6, s40, 0x80
	s_addc_u32 s7, s41, 0
	s_add_u32 s70, s38, 0x100
	s_addc_u32 s71, s39, 0
	v_mad_u64_u32 v[2:3], s[38:39], s36, v197, v[204:205]
	v_mov_b32_e32 v3, v1
	v_lshl_add_u64 v[130:131], s[8:9], 0, v[2:3]
	v_mad_u64_u32 v[2:3], s[38:39], v248, s36, v[204:205]
	v_mov_b32_e32 v3, v1
	v_mov_b32_e32 v26, 0
	v_mov_b64_e32 v[230:231], 0x200
	v_lshl_add_u64 v[132:133], s[8:9], 0, v[2:3]
	s_mov_b32 s72, 0
	v_mov_b32_e32 v27, v26
	v_mov_b32_e32 v28, v26
	v_mov_b32_e32 v29, v26
	v_mov_b32_e32 v30, v26
	v_mov_b32_e32 v31, v26
	v_mov_b32_e32 v32, v26
	v_mov_b32_e32 v33, v26
	s_waitcnt vmcnt(0)
	v_mov_b64_e32 v[42:43], 0
	v_mov_b64_e32 v[44:45], 0
	v_mov_b64_e32 v[46:47], 0
	v_mov_b64_e32 v[48:49], 0
	v_mov_b64_e32 v[58:59], 0
	v_mov_b64_e32 v[60:61], 0
	v_mov_b64_e32 v[62:63], 0
	v_mov_b64_e32 v[64:65], 0
	v_mov_b64_e32 v[66:67], 0
	v_mov_b64_e32 v[68:69], 0
	v_mov_b64_e32 v[70:71], 0
	v_mov_b64_e32 v[72:73], 0
	v_mov_b64_e32 v[82:83], 0
	v_mov_b64_e32 v[84:85], 0
	v_mov_b64_e32 v[86:87], 0
	v_mov_b64_e32 v[88:89], 0
	v_mov_b64_e32 v[98:99], 0
	v_mov_b64_e32 v[100:101], 0
	v_mov_b64_e32 v[102:103], 0
	v_mov_b64_e32 v[104:105], 0
	v_mov_b64_e32 v[114:115], 0
	v_mov_b64_e32 v[116:117], 0
	v_mov_b64_e32 v[118:119], 0
	v_mov_b64_e32 v[120:121], 0
	v_mov_b64_e32 v[74:75], 0
	v_mov_b64_e32 v[76:77], 0
	v_mov_b64_e32 v[78:79], 0
	v_mov_b64_e32 v[80:81], 0
	v_mov_b64_e32 v[90:91], 0
	v_mov_b64_e32 v[92:93], 0
	v_mov_b64_e32 v[94:95], 0
	v_mov_b64_e32 v[96:97], 0
	v_mov_b64_e32 v[106:107], 0
	v_mov_b64_e32 v[108:109], 0
	v_mov_b64_e32 v[110:111], 0
	v_mov_b64_e32 v[112:113], 0
	v_mov_b64_e32 v[122:123], 0
	v_mov_b64_e32 v[124:125], 0
	v_mov_b64_e32 v[126:127], 0
	v_mov_b64_e32 v[128:129], 0
	v_mov_b64_e32 v[14:15], 0
	v_mov_b64_e32 v[16:17], 0
	v_mov_b64_e32 v[10:11], 0
	v_mov_b64_e32 v[12:13], 0
	v_mov_b64_e32 v[54:55], 0
	v_mov_b64_e32 v[56:57], 0
	v_mov_b64_e32 v[50:51], 0
	v_mov_b64_e32 v[52:53], 0
	v_mov_b64_e32 v[38:39], 0
	v_mov_b64_e32 v[40:41], 0
	v_mov_b64_e32 v[34:35], 0
	v_mov_b64_e32 v[36:37], 0
	v_mov_b64_e32 v[22:23], 0
	v_mov_b64_e32 v[24:25], 0
	v_mov_b64_e32 v[18:19], 0
	v_mov_b64_e32 v[20:21], 0
	v_mov_b64_e32 v[6:7], 0
	v_mov_b64_e32 v[8:9], 0
	v_mov_b64_e32 v[2:3], 0
	v_mov_b64_e32 v[4:5], 0

; #define PG8_BAR __builtin_amdgcn_s_barrier()
; #define PG8_BAR __builtin_amdgcn_s_barrier()
; template <class Epi>
; __device__ __forceinline__ void gemm_merge_fused(LAS unsigned char* lds, const bf16_t* Yb, const bf16_t* XBb, const bf16_t* WBR, const bf16_t* WG, const MergeOrder& S, const Epi& E) {
;     ...
; #pragma unroll
;         for (int a = 0; a < 2; ++a)
; #pragma unroll
;             for (int b = 0; b < 2; ++b)
; #pragma unroll
;                 for (int m = 0; m < 4; ++m)
; #pragma unroll
;                     for (int n = 0; n < 2; ++n) acc[a][b][m][n] = (f32x4){0.f, 0.f, 0.f, 0.f};
;         cur = nxt; cA = nA; cB = nB; ck = nk; ++ui;
;         if (wr == 1) PG8_BAR;
.LBB0_1388:
	v_mov_b32_e32 v5, 0
	v_mov_b32_e32 v4, v5
	v_mov_b32_e32 v3, v5
	v_mov_b32_e32 v2, v5
	v_mov_b32_e32 v9, v5
	v_mov_b32_e32 v8, v5
	v_mov_b32_e32 v7, v5
	v_mov_b32_e32 v6, v5
	v_mov_b32_e32 v21, v5
	v_mov_b32_e32 v20, v5
	v_mov_b32_e32 v19, v5
	v_mov_b32_e32 v18, v5
	v_mov_b32_e32 v25, v5
	v_mov_b32_e32 v24, v5
	v_mov_b32_e32 v23, v5
	v_mov_b32_e32 v22, v5
	s_waitcnt vmcnt(0)
	v_mov_b64_e32 v[36:37], 0
	v_mov_b64_e32 v[34:35], 0
	v_mov_b64_e32 v[40:41], 0
	v_mov_b64_e32 v[38:39], 0
	v_mov_b64_e32 v[52:53], 0
	v_mov_b64_e32 v[50:51], 0
	v_mov_b64_e32 v[56:57], 0
	v_mov_b64_e32 v[54:55], 0
	v_mov_b64_e32 v[12:13], 0
	v_mov_b64_e32 v[10:11], 0
	v_mov_b64_e32 v[16:17], 0
	v_mov_b64_e32 v[14:15], 0
	v_mov_b64_e32 v[128:129], 0
	v_mov_b64_e32 v[126:127], 0
	v_mov_b64_e32 v[124:125], 0
	v_mov_b64_e32 v[122:123], 0
	v_mov_b64_e32 v[112:113], 0
	v_mov_b64_e32 v[110:111], 0
	v_mov_b64_e32 v[108:109], 0
	v_mov_b64_e32 v[106:107], 0
	v_mov_b64_e32 v[96:97], 0
	v_mov_b64_e32 v[94:95], 0
	v_mov_b64_e32 v[92:93], 0
	v_mov_b64_e32 v[90:91], 0
	v_mov_b64_e32 v[80:81], 0
	v_mov_b64_e32 v[78:79], 0
	v_mov_b64_e32 v[76:77], 0
	v_mov_b64_e32 v[74:75], 0
	v_mov_b64_e32 v[120:121], 0
	v_mov_b64_e32 v[118:119], 0
	v_mov_b64_e32 v[116:117], 0
	v_mov_b64_e32 v[114:115], 0
	v_mov_b64_e32 v[104:105], 0
	v_mov_b64_e32 v[102:103], 0
	v_mov_b64_e32 v[100:101], 0
	v_mov_b64_e32 v[98:99], 0
	v_mov_b64_e32 v[88:89], 0
	v_mov_b64_e32 v[86:87], 0
	v_mov_b64_e32 v[84:85], 0
	v_mov_b64_e32 v[82:83], 0
	v_mov_b64_e32 v[72:73], 0
	v_mov_b64_e32 v[70:71], 0
	v_mov_b64_e32 v[68:69], 0
	v_mov_b64_e32 v[66:67], 0
	v_mov_b64_e32 v[64:65], 0
	v_mov_b64_e32 v[62:63], 0
	v_mov_b64_e32 v[60:61], 0
	v_mov_b64_e32 v[58:59], 0
	v_mov_b64_e32 v[48:49], 0
	v_mov_b64_e32 v[46:47], 0
	v_mov_b64_e32 v[44:45], 0
	v_mov_b64_e32 v[42:43], 0
	v_mov_b64_e32 v[32:33], 0
	v_mov_b64_e32 v[30:31], 0
	v_mov_b64_e32 v[28:29], 0
	v_mov_b64_e32 v[26:27], 0
	v_mov_b64_e32 v[222:223], 0x1ff
	s_and_b64 vcc, exec, s[18:19]
	s_cbranch_vccnz .LBB0_1333
	s_branch .LBB0_1334

; template <class Epi, class Sched>
; __device__ __forceinline__ void gemm_phase(LAS unsigned char* lds, const Gemm g, const Sched& S, const Epi& E) {
;     ...
;     f32x4 acc[2][2][4][2];
; #pragma unroll
;     for (int a = 0; a < 2; ++a)
; #pragma unroll
;         for (int b = 0; b < 2; ++b)
; #pragma unroll
;             for (int m = 0; m < 4; ++m)
; #pragma unroll
;                 for (int n = 0; n < 2; ++n) acc[a][b][m][n] = (f32x4){0.f, 0.f, 0.f, 0.f};
;     ...
;         for (int a = 0; a < 2; ++a)
; #pragma unroll
;             for (int b = 0; b < 2; ++b)
; #pragma unroll
;                 for (int m = 0; m < 4; ++m)
; #pragma unroll
;                     for (int n = 0; n < 2; ++n) acc[a][b][m][n] = (f32x4){0.f, 0.f, 0.f, 0.f};
.LBB0_1461:
	v_mov_b32_e32 v125, 0
	s_andn2_b64 vcc, exec, s[26:27]
	v_mov_b32_e32 v124, v125
	v_mov_b64_e32 v[122:123], 0
	v_mov_b64_e32 v[128:129], 0
	v_mov_b64_e32 v[126:127], 0
	v_mov_b64_e32 v[112:113], 0
	v_mov_b64_e32 v[110:111], 0
	v_mov_b64_e32 v[108:109], 0
	v_mov_b64_e32 v[106:107], 0
	v_mov_b64_e32 v[96:97], 0
	v_mov_b64_e32 v[94:95], 0
	v_mov_b64_e32 v[92:93], 0
	v_mov_b64_e32 v[90:91], 0
	v_mov_b64_e32 v[80:81], 0
	v_mov_b64_e32 v[78:79], 0
	v_mov_b64_e32 v[76:77], 0
	v_mov_b64_e32 v[74:75], 0
	v_mov_b64_e32 v[120:121], 0
	v_mov_b64_e32 v[118:119], 0
	v_mov_b64_e32 v[116:117], 0
	v_mov_b64_e32 v[114:115], 0
	v_mov_b64_e32 v[104:105], 0
	v_mov_b64_e32 v[102:103], 0
	v_mov_b64_e32 v[100:101], 0
	v_mov_b64_e32 v[98:99], 0
	v_mov_b64_e32 v[88:89], 0
	v_mov_b64_e32 v[86:87], 0
	v_mov_b64_e32 v[84:85], 0
	v_mov_b64_e32 v[82:83], 0
	v_mov_b64_e32 v[72:73], 0
	v_mov_b64_e32 v[70:71], 0
	v_mov_b64_e32 v[68:69], 0
	v_mov_b64_e32 v[66:67], 0
	v_mov_b64_e32 v[64:65], 0
	v_mov_b64_e32 v[62:63], 0
	v_mov_b64_e32 v[60:61], 0
	v_mov_b64_e32 v[58:59], 0
	v_mov_b64_e32 v[48:49], 0
	v_mov_b64_e32 v[46:47], 0
	v_mov_b64_e32 v[44:45], 0
	v_mov_b64_e32 v[42:43], 0
	v_mov_b64_e32 v[32:33], 0
	v_mov_b64_e32 v[30:31], 0
	v_mov_b64_e32 v[28:29], 0
	v_mov_b64_e32 v[26:27], 0
	v_mov_b64_e32 v[16:17], 0
	v_mov_b64_e32 v[14:15], 0
	v_mov_b64_e32 v[12:13], 0
	v_mov_b64_e32 v[10:11], 0
	v_mov_b64_e32 v[56:57], 0
	v_mov_b64_e32 v[54:55], 0
	v_mov_b64_e32 v[52:53], 0
	v_mov_b64_e32 v[50:51], 0
	v_mov_b64_e32 v[40:41], 0
	v_mov_b64_e32 v[38:39], 0
	v_mov_b64_e32 v[36:37], 0
	v_mov_b64_e32 v[34:35], 0
	v_mov_b64_e32 v[24:25], 0
	v_mov_b64_e32 v[22:23], 0
	v_mov_b64_e32 v[20:21], 0
	v_mov_b64_e32 v[18:19], 0
	v_mov_b64_e32 v[8:9], 0
	v_mov_b64_e32 v[6:7], 0
	v_mov_b64_e32 v[4:5], 0
	v_mov_b64_e32 v[2:3], 0
	s_cbranch_vccnz .LBB0_1464
	s_add_u32 s0, s0, 0x80
	s_addc_u32 s1, s1, 0
	s_add_u32 s63, s38, 0x100
	v_mov_b32_e32 v2, 0
	s_addc_u32 s64, s39, 0
	s_mov_b32 s38, 0
	v_mov_b32_e32 v3, v2
	v_mov_b64_e32 v[4:5], 0
	v_mov_b64_e32 v[6:7], 0
	v_mov_b64_e32 v[8:9], 0
	v_mov_b64_e32 v[18:19], 0
	v_mov_b64_e32 v[20:21], 0
	v_mov_b64_e32 v[22:23], 0
	v_mov_b64_e32 v[24:25], 0
	v_mov_b64_e32 v[34:35], 0
	v_mov_b64_e32 v[36:37], 0
	v_mov_b64_e32 v[38:39], 0
	v_mov_b64_e32 v[40:41], 0
	v_mov_b64_e32 v[50:51], 0
	v_mov_b64_e32 v[52:53], 0
	v_mov_b64_e32 v[54:55], 0
	v_mov_b64_e32 v[56:57], 0
	v_mov_b64_e32 v[10:11], 0
	v_mov_b64_e32 v[12:13], 0
	v_mov_b64_e32 v[14:15], 0
	v_mov_b64_e32 v[16:17], 0
	v_mov_b64_e32 v[26:27], 0
	v_mov_b64_e32 v[28:29], 0
	v_mov_b64_e32 v[30:31], 0
	v_mov_b64_e32 v[32:33], 0
	v_mov_b64_e32 v[42:43], 0
	v_mov_b64_e32 v[44:45], 0
	v_mov_b64_e32 v[46:47], 0
	v_mov_b64_e32 v[48:49], 0
	v_mov_b64_e32 v[58:59], 0
	v_mov_b64_e32 v[60:61], 0
	v_mov_b64_e32 v[62:63], 0
	v_mov_b64_e32 v[64:65], 0
	v_mov_b64_e32 v[66:67], 0
	v_mov_b64_e32 v[68:69], 0
	v_mov_b64_e32 v[70:71], 0
	v_mov_b64_e32 v[72:73], 0
	v_mov_b64_e32 v[82:83], 0
	v_mov_b64_e32 v[84:85], 0
	v_mov_b64_e32 v[86:87], 0
	v_mov_b64_e32 v[88:89], 0
	v_mov_b64_e32 v[98:99], 0
	v_mov_b64_e32 v[100:101], 0
	v_mov_b64_e32 v[102:103], 0
	v_mov_b64_e32 v[104:105], 0
	v_mov_b64_e32 v[114:115], 0
	v_mov_b64_e32 v[116:117], 0
	v_mov_b64_e32 v[118:119], 0
	v_mov_b64_e32 v[120:121], 0
	v_mov_b64_e32 v[74:75], 0
	v_mov_b64_e32 v[76:77], 0
	v_mov_b64_e32 v[78:79], 0
	v_mov_b64_e32 v[80:81], 0
	v_mov_b64_e32 v[90:91], 0
	v_mov_b64_e32 v[92:93], 0
	v_mov_b64_e32 v[94:95], 0
	v_mov_b64_e32 v[96:97], 0
	v_mov_b64_e32 v[106:107], 0
	v_mov_b64_e32 v[108:109], 0
	v_mov_b64_e32 v[110:111], 0
	v_mov_b64_e32 v[112:113], 0
	v_mov_b64_e32 v[126:127], 0
	v_mov_b64_e32 v[128:129], 0
	v_mov_b64_e32 v[122:123], 0
	v_mov_b64_e32 v[124:125], 0

; template <class Epi, class Sched>
; __device__ __forceinline__ void gemm_phase(LAS unsigned char* lds, const Gemm g, const Sched& S, const Epi& E) {
;     ...
;     f32x4 acc[2][2][4][2];
; #pragma unroll
;     for (int a = 0; a < 2; ++a)
; #pragma unroll
;         for (int b = 0; b < 2; ++b)
; #pragma unroll
;             for (int m = 0; m < 4; ++m)
; #pragma unroll
;                 for (int n = 0; n < 2; ++n) acc[a][b][m][n] = (f32x4){0.f, 0.f, 0.f, 0.f};
;     ...
;         for (int a = 0; a < 2; ++a)
; #pragma unroll
;             for (int b = 0; b < 2; ++b)
; #pragma unroll
;                 for (int m = 0; m < 4; ++m)
; #pragma unroll
;                     for (int n = 0; n < 2; ++n) acc[a][b][m][n] = (f32x4){0.f, 0.f, 0.f, 0.f};
.LBB0_1566:
	v_mov_b32_e32 v125, 0
	s_andn2_b64 vcc, exec, s[20:21]
	v_mov_b32_e32 v124, v125
	v_mov_b64_e32 v[122:123], 0
	v_mov_b64_e32 v[128:129], 0
	v_mov_b64_e32 v[126:127], 0
	v_mov_b64_e32 v[112:113], 0
	v_mov_b64_e32 v[110:111], 0
	v_mov_b64_e32 v[108:109], 0
	v_mov_b64_e32 v[106:107], 0
	v_mov_b64_e32 v[96:97], 0
	v_mov_b64_e32 v[94:95], 0
	v_mov_b64_e32 v[92:93], 0
	v_mov_b64_e32 v[90:91], 0
	v_mov_b64_e32 v[80:81], 0
	v_mov_b64_e32 v[78:79], 0
	v_mov_b64_e32 v[76:77], 0
	v_mov_b64_e32 v[74:75], 0
	v_mov_b64_e32 v[120:121], 0
	v_mov_b64_e32 v[118:119], 0
	v_mov_b64_e32 v[116:117], 0
	v_mov_b64_e32 v[114:115], 0
	v_mov_b64_e32 v[104:105], 0
	v_mov_b64_e32 v[102:103], 0
	v_mov_b64_e32 v[100:101], 0
	v_mov_b64_e32 v[98:99], 0
	v_mov_b64_e32 v[88:89], 0
	v_mov_b64_e32 v[86:87], 0
	v_mov_b64_e32 v[84:85], 0
	v_mov_b64_e32 v[82:83], 0
	v_mov_b64_e32 v[72:73], 0
	v_mov_b64_e32 v[70:71], 0
	v_mov_b64_e32 v[68:69], 0
	v_mov_b64_e32 v[66:67], 0
	v_mov_b64_e32 v[64:65], 0
	v_mov_b64_e32 v[62:63], 0
	v_mov_b64_e32 v[60:61], 0
	v_mov_b64_e32 v[58:59], 0
	v_mov_b64_e32 v[48:49], 0
	v_mov_b64_e32 v[46:47], 0
	v_mov_b64_e32 v[44:45], 0
	v_mov_b64_e32 v[42:43], 0
	v_mov_b64_e32 v[32:33], 0
	v_mov_b64_e32 v[30:31], 0
	v_mov_b64_e32 v[28:29], 0
	v_mov_b64_e32 v[26:27], 0
	v_mov_b64_e32 v[16:17], 0
	v_mov_b64_e32 v[14:15], 0
	v_mov_b64_e32 v[12:13], 0
	v_mov_b64_e32 v[10:11], 0
	v_mov_b64_e32 v[56:57], 0
	v_mov_b64_e32 v[54:55], 0
	v_mov_b64_e32 v[52:53], 0
	v_mov_b64_e32 v[50:51], 0
	v_mov_b64_e32 v[40:41], 0
	v_mov_b64_e32 v[38:39], 0
	v_mov_b64_e32 v[36:37], 0
	v_mov_b64_e32 v[34:35], 0
	v_mov_b64_e32 v[24:25], 0
	v_mov_b64_e32 v[22:23], 0
	v_mov_b64_e32 v[20:21], 0
	v_mov_b64_e32 v[18:19], 0
	v_mov_b64_e32 v[8:9], 0
	v_mov_b64_e32 v[6:7], 0
	v_mov_b64_e32 v[4:5], 0
	v_mov_b64_e32 v[2:3], 0
	s_cbranch_vccnz .LBB0_1569
	s_add_u32 s26, s26, 0x80
	s_addc_u32 s27, s27, 0
	s_add_u32 s58, s28, 0x100
	v_mov_b32_e32 v2, 0
	s_addc_u32 s59, s29, 0
	s_mov_b32 s28, 0
	v_mov_b32_e32 v3, v2
	v_mov_b64_e32 v[4:5], 0
	v_mov_b64_e32 v[6:7], 0
	v_mov_b64_e32 v[8:9], 0
	v_mov_b64_e32 v[18:19], 0
	v_mov_b64_e32 v[20:21], 0
	v_mov_b64_e32 v[22:23], 0
	v_mov_b64_e32 v[24:25], 0
	v_mov_b64_e32 v[34:35], 0
	v_mov_b64_e32 v[36:37], 0
	v_mov_b64_e32 v[38:39], 0
	v_mov_b64_e32 v[40:41], 0
	v_mov_b64_e32 v[50:51], 0
	v_mov_b64_e32 v[52:53], 0
	v_mov_b64_e32 v[54:55], 0
	v_mov_b64_e32 v[56:57], 0
	v_mov_b64_e32 v[10:11], 0
	v_mov_b64_e32 v[12:13], 0
	v_mov_b64_e32 v[14:15], 0
	v_mov_b64_e32 v[16:17], 0
	v_mov_b64_e32 v[26:27], 0
	v_mov_b64_e32 v[28:29], 0
	v_mov_b64_e32 v[30:31], 0
	v_mov_b64_e32 v[32:33], 0
	v_mov_b64_e32 v[42:43], 0
	v_mov_b64_e32 v[44:45], 0
	v_mov_b64_e32 v[46:47], 0
	v_mov_b64_e32 v[48:49], 0
	v_mov_b64_e32 v[58:59], 0
	v_mov_b64_e32 v[60:61], 0
	v_mov_b64_e32 v[62:63], 0
	v_mov_b64_e32 v[64:65], 0
	v_mov_b64_e32 v[66:67], 0
	v_mov_b64_e32 v[68:69], 0
	v_mov_b64_e32 v[70:71], 0
	v_mov_b64_e32 v[72:73], 0
	v_mov_b64_e32 v[82:83], 0
	v_mov_b64_e32 v[84:85], 0
	v_mov_b64_e32 v[86:87], 0
	v_mov_b64_e32 v[88:89], 0
	v_mov_b64_e32 v[98:99], 0
	v_mov_b64_e32 v[100:101], 0
	v_mov_b64_e32 v[102:103], 0
	v_mov_b64_e32 v[104:105], 0
	v_mov_b64_e32 v[114:115], 0
	v_mov_b64_e32 v[116:117], 0
	v_mov_b64_e32 v[118:119], 0
	v_mov_b64_e32 v[120:121], 0
	v_mov_b64_e32 v[74:75], 0
	v_mov_b64_e32 v[76:77], 0
	v_mov_b64_e32 v[78:79], 0
	v_mov_b64_e32 v[80:81], 0
	v_mov_b64_e32 v[90:91], 0
	v_mov_b64_e32 v[92:93], 0
	v_mov_b64_e32 v[94:95], 0
	v_mov_b64_e32 v[96:97], 0
	v_mov_b64_e32 v[106:107], 0
	v_mov_b64_e32 v[108:109], 0
	v_mov_b64_e32 v[110:111], 0
	v_mov_b64_e32 v[112:113], 0
	v_mov_b64_e32 v[126:127], 0
	v_mov_b64_e32 v[128:129], 0
	v_mov_b64_e32 v[122:123], 0
	v_mov_b64_e32 v[124:125], 0

; template <class Epi, class Sched>
; __device__ __forceinline__ void gemm_phase(LAS unsigned char* lds, const Gemm g, const Sched& S, const Epi& E) {
;     ...
;     f32x4 acc[2][2][4][2];
; #pragma unroll
;     for (int a = 0; a < 2; ++a)
; #pragma unroll
;         for (int b = 0; b < 2; ++b)
; #pragma unroll
;             for (int m = 0; m < 4; ++m)
; #pragma unroll
;                 for (int n = 0; n < 2; ++n) acc[a][b][m][n] = (f32x4){0.f, 0.f, 0.f, 0.f};
;     ...
;         for (int a = 0; a < 2; ++a)
; #pragma unroll
;             for (int b = 0; b < 2; ++b)
; #pragma unroll
;                 for (int m = 0; m < 4; ++m)
; #pragma unroll
;                     for (int n = 0; n < 2; ++n) acc[a][b][m][n] = (f32x4){0.f, 0.f, 0.f, 0.f};
.LBB0_1643:
	v_mov_b32_e32 v125, 0
	s_andn2_b64 vcc, exec, s[26:27]
	v_mov_b32_e32 v124, v125
	v_mov_b64_e32 v[122:123], 0
	v_mov_b64_e32 v[128:129], 0
	v_mov_b64_e32 v[126:127], 0
	v_mov_b64_e32 v[112:113], 0
	v_mov_b64_e32 v[110:111], 0
	v_mov_b64_e32 v[108:109], 0
	v_mov_b64_e32 v[106:107], 0
	v_mov_b64_e32 v[96:97], 0
	v_mov_b64_e32 v[94:95], 0
	v_mov_b64_e32 v[92:93], 0
	v_mov_b64_e32 v[90:91], 0
	v_mov_b64_e32 v[80:81], 0
	v_mov_b64_e32 v[78:79], 0
	v_mov_b64_e32 v[76:77], 0
	v_mov_b64_e32 v[74:75], 0
	v_mov_b64_e32 v[120:121], 0
	v_mov_b64_e32 v[118:119], 0
	v_mov_b64_e32 v[116:117], 0
	v_mov_b64_e32 v[114:115], 0
	v_mov_b64_e32 v[104:105], 0
	v_mov_b64_e32 v[102:103], 0
	v_mov_b64_e32 v[100:101], 0
	v_mov_b64_e32 v[98:99], 0
	v_mov_b64_e32 v[88:89], 0
	v_mov_b64_e32 v[86:87], 0
	v_mov_b64_e32 v[84:85], 0
	v_mov_b64_e32 v[82:83], 0
	v_mov_b64_e32 v[72:73], 0
	v_mov_b64_e32 v[70:71], 0
	v_mov_b64_e32 v[68:69], 0
	v_mov_b64_e32 v[66:67], 0
	v_mov_b64_e32 v[64:65], 0
	v_mov_b64_e32 v[62:63], 0
	v_mov_b64_e32 v[60:61], 0
	v_mov_b64_e32 v[58:59], 0
	v_mov_b64_e32 v[48:49], 0
	v_mov_b64_e32 v[46:47], 0
	v_mov_b64_e32 v[44:45], 0
	v_mov_b64_e32 v[42:43], 0
	v_mov_b64_e32 v[32:33], 0
	v_mov_b64_e32 v[30:31], 0
	v_mov_b64_e32 v[28:29], 0
	v_mov_b64_e32 v[26:27], 0
	v_mov_b64_e32 v[16:17], 0
	v_mov_b64_e32 v[14:15], 0
	v_mov_b64_e32 v[12:13], 0
	v_mov_b64_e32 v[10:11], 0
	v_mov_b64_e32 v[56:57], 0
	v_mov_b64_e32 v[54:55], 0
	v_mov_b64_e32 v[52:53], 0
	v_mov_b64_e32 v[50:51], 0
	v_mov_b64_e32 v[40:41], 0
	v_mov_b64_e32 v[38:39], 0
	v_mov_b64_e32 v[36:37], 0
	v_mov_b64_e32 v[34:35], 0
	v_mov_b64_e32 v[24:25], 0
	v_mov_b64_e32 v[22:23], 0
	v_mov_b64_e32 v[20:21], 0
	v_mov_b64_e32 v[18:19], 0
	v_mov_b64_e32 v[8:9], 0
	v_mov_b64_e32 v[6:7], 0
	v_mov_b64_e32 v[4:5], 0
	v_mov_b64_e32 v[2:3], 0
	s_cbranch_vccnz .LBB0_1646
	s_add_u32 s38, s38, 0x80
	s_addc_u32 s39, s39, 0
	s_add_u32 s64, s40, 0x100
	v_mov_b32_e32 v2, 0
	s_addc_u32 s65, s41, 0
	s_mov_b32 s40, 0
	v_mov_b32_e32 v3, v2
	v_mov_b64_e32 v[4:5], 0
	v_mov_b64_e32 v[6:7], 0
	v_mov_b64_e32 v[8:9], 0
	v_mov_b64_e32 v[18:19], 0
	v_mov_b64_e32 v[20:21], 0
	v_mov_b64_e32 v[22:23], 0
	v_mov_b64_e32 v[24:25], 0
	v_mov_b64_e32 v[34:35], 0
	v_mov_b64_e32 v[36:37], 0
	v_mov_b64_e32 v[38:39], 0
	v_mov_b64_e32 v[40:41], 0
	v_mov_b64_e32 v[50:51], 0
	v_mov_b64_e32 v[52:53], 0
	v_mov_b64_e32 v[54:55], 0
	v_mov_b64_e32 v[56:57], 0
	v_mov_b64_e32 v[10:11], 0
	v_mov_b64_e32 v[12:13], 0
	v_mov_b64_e32 v[14:15], 0
	v_mov_b64_e32 v[16:17], 0
	v_mov_b64_e32 v[26:27], 0
	v_mov_b64_e32 v[28:29], 0
	v_mov_b64_e32 v[30:31], 0
	v_mov_b64_e32 v[32:33], 0
	v_mov_b64_e32 v[42:43], 0
	v_mov_b64_e32 v[44:45], 0
	v_mov_b64_e32 v[46:47], 0
	v_mov_b64_e32 v[48:49], 0
	v_mov_b64_e32 v[58:59], 0
	v_mov_b64_e32 v[60:61], 0
	v_mov_b64_e32 v[62:63], 0
	v_mov_b64_e32 v[64:65], 0
	v_mov_b64_e32 v[66:67], 0
	v_mov_b64_e32 v[68:69], 0
	v_mov_b64_e32 v[70:71], 0
	v_mov_b64_e32 v[72:73], 0
	v_mov_b64_e32 v[82:83], 0
	v_mov_b64_e32 v[84:85], 0
	v_mov_b64_e32 v[86:87], 0
	v_mov_b64_e32 v[88:89], 0
	v_mov_b64_e32 v[98:99], 0
	v_mov_b64_e32 v[100:101], 0
	v_mov_b64_e32 v[102:103], 0
	v_mov_b64_e32 v[104:105], 0
	v_mov_b64_e32 v[114:115], 0
	v_mov_b64_e32 v[116:117], 0
	v_mov_b64_e32 v[118:119], 0
	v_mov_b64_e32 v[120:121], 0
	v_mov_b64_e32 v[74:75], 0
	v_mov_b64_e32 v[76:77], 0
	v_mov_b64_e32 v[78:79], 0
	v_mov_b64_e32 v[80:81], 0
	v_mov_b64_e32 v[90:91], 0
	v_mov_b64_e32 v[92:93], 0
	v_mov_b64_e32 v[94:95], 0
	v_mov_b64_e32 v[96:97], 0
	v_mov_b64_e32 v[106:107], 0
	v_mov_b64_e32 v[108:109], 0
	v_mov_b64_e32 v[110:111], 0
	v_mov_b64_e32 v[112:113], 0
	v_mov_b64_e32 v[126:127], 0
	v_mov_b64_e32 v[128:129], 0
	v_mov_b64_e32 v[122:123], 0
	v_mov_b64_e32 v[124:125], 0

; template <class Epi, class Sched>
; __device__ __forceinline__ void gemm_phase(LAS unsigned char* lds, const Gemm g, const Sched& S, const Epi& E) {
;     ...
;     f32x4 acc[2][2][4][2];
; #pragma unroll
;     for (int a = 0; a < 2; ++a)
; #pragma unroll
;         for (int b = 0; b < 2; ++b)
; #pragma unroll
;             for (int m = 0; m < 4; ++m)
; #pragma unroll
;                 for (int n = 0; n < 2; ++n) acc[a][b][m][n] = (f32x4){0.f, 0.f, 0.f, 0.f};
;     ...
;         for (int a = 0; a < 2; ++a)
; #pragma unroll
;             for (int b = 0; b < 2; ++b)
; #pragma unroll
;                 for (int m = 0; m < 4; ++m)
; #pragma unroll
;                     for (int n = 0; n < 2; ++n) acc[a][b][m][n] = (f32x4){0.f, 0.f, 0.f, 0.f};
.LBB0_1684:
	v_mov_b32_e32 v125, 0
	s_andn2_b64 vcc, exec, s[20:21]
	v_mov_b32_e32 v124, v125
	v_mov_b64_e32 v[122:123], 0
	v_mov_b64_e32 v[128:129], 0
	v_mov_b64_e32 v[126:127], 0
	v_mov_b64_e32 v[112:113], 0
	v_mov_b64_e32 v[110:111], 0
	v_mov_b64_e32 v[108:109], 0
	v_mov_b64_e32 v[106:107], 0
	v_mov_b64_e32 v[96:97], 0
	v_mov_b64_e32 v[94:95], 0
	v_mov_b64_e32 v[92:93], 0
	v_mov_b64_e32 v[90:91], 0
	v_mov_b64_e32 v[80:81], 0
	v_mov_b64_e32 v[78:79], 0
	v_mov_b64_e32 v[76:77], 0
	v_mov_b64_e32 v[74:75], 0
	v_mov_b64_e32 v[120:121], 0
	v_mov_b64_e32 v[118:119], 0
	v_mov_b64_e32 v[116:117], 0
	v_mov_b64_e32 v[114:115], 0
	v_mov_b64_e32 v[104:105], 0
	v_mov_b64_e32 v[102:103], 0
	v_mov_b64_e32 v[100:101], 0
	v_mov_b64_e32 v[98:99], 0
	v_mov_b64_e32 v[88:89], 0
	v_mov_b64_e32 v[86:87], 0
	v_mov_b64_e32 v[84:85], 0
	v_mov_b64_e32 v[82:83], 0
	v_mov_b64_e32 v[72:73], 0
	v_mov_b64_e32 v[70:71], 0
	v_mov_b64_e32 v[68:69], 0
	v_mov_b64_e32 v[66:67], 0
	v_mov_b64_e32 v[64:65], 0
	v_mov_b64_e32 v[62:63], 0
	v_mov_b64_e32 v[60:61], 0
	v_mov_b64_e32 v[58:59], 0
	v_mov_b64_e32 v[48:49], 0
	v_mov_b64_e32 v[46:47], 0
	v_mov_b64_e32 v[44:45], 0
	v_mov_b64_e32 v[42:43], 0
	v_mov_b64_e32 v[32:33], 0
	v_mov_b64_e32 v[30:31], 0
	v_mov_b64_e32 v[28:29], 0
	v_mov_b64_e32 v[26:27], 0
	v_mov_b64_e32 v[16:17], 0
	v_mov_b64_e32 v[14:15], 0
	v_mov_b64_e32 v[12:13], 0
	v_mov_b64_e32 v[10:11], 0
	v_mov_b64_e32 v[56:57], 0
	v_mov_b64_e32 v[54:55], 0
	v_mov_b64_e32 v[52:53], 0
	v_mov_b64_e32 v[50:51], 0
	v_mov_b64_e32 v[40:41], 0
	v_mov_b64_e32 v[38:39], 0
	v_mov_b64_e32 v[36:37], 0
	v_mov_b64_e32 v[34:35], 0
	v_mov_b64_e32 v[24:25], 0
	v_mov_b64_e32 v[22:23], 0
	v_mov_b64_e32 v[20:21], 0
	v_mov_b64_e32 v[18:19], 0
	v_mov_b64_e32 v[8:9], 0
	v_mov_b64_e32 v[6:7], 0
	v_mov_b64_e32 v[4:5], 0
	v_mov_b64_e32 v[2:3], 0
	s_cbranch_vccnz .LBB0_1688
	s_add_u32 s26, s26, 0x80
	s_addc_u32 s27, s27, 0
	s_add_u32 s55, s28, 0x100
	v_mov_b32_e32 v2, 0
	s_addc_u32 s56, s29, 0
	s_mov_b32 s28, 0
	v_mov_b32_e32 v3, v2
	v_mov_b64_e32 v[4:5], 0
	v_mov_b64_e32 v[6:7], 0
	v_mov_b64_e32 v[8:9], 0
	v_mov_b64_e32 v[18:19], 0
	v_mov_b64_e32 v[20:21], 0
	v_mov_b64_e32 v[22:23], 0
	v_mov_b64_e32 v[24:25], 0
	v_mov_b64_e32 v[34:35], 0
	v_mov_b64_e32 v[36:37], 0
	v_mov_b64_e32 v[38:39], 0
	v_mov_b64_e32 v[40:41], 0
	v_mov_b64_e32 v[50:51], 0
	v_mov_b64_e32 v[52:53], 0
	v_mov_b64_e32 v[54:55], 0
	v_mov_b64_e32 v[56:57], 0
	v_mov_b64_e32 v[10:11], 0
	v_mov_b64_e32 v[12:13], 0
	v_mov_b64_e32 v[14:15], 0
	v_mov_b64_e32 v[16:17], 0
	v_mov_b64_e32 v[26:27], 0
	v_mov_b64_e32 v[28:29], 0
	v_mov_b64_e32 v[30:31], 0
	v_mov_b64_e32 v[32:33], 0
	v_mov_b64_e32 v[42:43], 0
	v_mov_b64_e32 v[44:45], 0
	v_mov_b64_e32 v[46:47], 0
	v_mov_b64_e32 v[48:49], 0
	v_mov_b64_e32 v[58:59], 0
	v_mov_b64_e32 v[60:61], 0
	v_mov_b64_e32 v[62:63], 0
	v_mov_b64_e32 v[64:65], 0
	v_mov_b64_e32 v[66:67], 0
	v_mov_b64_e32 v[68:69], 0
	v_mov_b64_e32 v[70:71], 0
	v_mov_b64_e32 v[72:73], 0
	v_mov_b64_e32 v[82:83], 0
	v_mov_b64_e32 v[84:85], 0
	v_mov_b64_e32 v[86:87], 0
	v_mov_b64_e32 v[88:89], 0
	v_mov_b64_e32 v[98:99], 0
	v_mov_b64_e32 v[100:101], 0
	v_mov_b64_e32 v[102:103], 0
	v_mov_b64_e32 v[104:105], 0
	v_mov_b64_e32 v[114:115], 0
	v_mov_b64_e32 v[116:117], 0
	v_mov_b64_e32 v[118:119], 0
	v_mov_b64_e32 v[120:121], 0
	v_mov_b64_e32 v[74:75], 0
	v_mov_b64_e32 v[76:77], 0
	v_mov_b64_e32 v[78:79], 0
	v_mov_b64_e32 v[80:81], 0
	v_mov_b64_e32 v[90:91], 0
	v_mov_b64_e32 v[92:93], 0
	v_mov_b64_e32 v[94:95], 0
	v_mov_b64_e32 v[96:97], 0
	v_mov_b64_e32 v[106:107], 0
	v_mov_b64_e32 v[108:109], 0
	v_mov_b64_e32 v[110:111], 0
	v_mov_b64_e32 v[112:113], 0
	v_mov_b64_e32 v[126:127], 0
	v_mov_b64_e32 v[128:129], 0
	v_mov_b64_e32 v[122:123], 0
	v_mov_b64_e32 v[124:125], 0

; template <class Epi, class Sched>
; __device__ __forceinline__ void gemm_phase(LAS unsigned char* lds, const Gemm g, const Sched& S, const Epi& E) {
;     ...
;     f32x4 acc[2][2][4][2];
; #pragma unroll
;     for (int a = 0; a < 2; ++a)
; #pragma unroll
;         for (int b = 0; b < 2; ++b)
; #pragma unroll
;             for (int m = 0; m < 4; ++m)
; #pragma unroll
;                 for (int n = 0; n < 2; ++n) acc[a][b][m][n] = (f32x4){0.f, 0.f, 0.f, 0.f};
;     ...
;         for (int a = 0; a < 2; ++a)
; #pragma unroll
;             for (int b = 0; b < 2; ++b)
; #pragma unroll
;                 for (int m = 0; m < 4; ++m)
; #pragma unroll
;                     for (int n = 0; n < 2; ++n) acc[a][b][m][n] = (f32x4){0.f, 0.f, 0.f, 0.f};
.LBB0_1771:
	v_mov_b32_e32 v125, 0
	s_andn2_b64 vcc, exec, s[22:23]
	v_mov_b32_e32 v124, v125
	v_mov_b64_e32 v[122:123], 0
	v_mov_b64_e32 v[128:129], 0
	v_mov_b64_e32 v[126:127], 0
	v_mov_b64_e32 v[112:113], 0
	v_mov_b64_e32 v[110:111], 0
	v_mov_b64_e32 v[108:109], 0
	v_mov_b64_e32 v[106:107], 0
	v_mov_b64_e32 v[96:97], 0
	v_mov_b64_e32 v[94:95], 0
	v_mov_b64_e32 v[92:93], 0
	v_mov_b64_e32 v[90:91], 0
	v_mov_b64_e32 v[80:81], 0
	v_mov_b64_e32 v[78:79], 0
	v_mov_b64_e32 v[76:77], 0
	v_mov_b64_e32 v[74:75], 0
	v_mov_b64_e32 v[120:121], 0
	v_mov_b64_e32 v[118:119], 0
	v_mov_b64_e32 v[116:117], 0
	v_mov_b64_e32 v[114:115], 0
	v_mov_b64_e32 v[104:105], 0
	v_mov_b64_e32 v[102:103], 0
	v_mov_b64_e32 v[100:101], 0
	v_mov_b64_e32 v[98:99], 0
	v_mov_b64_e32 v[88:89], 0
	v_mov_b64_e32 v[86:87], 0
	v_mov_b64_e32 v[84:85], 0
	v_mov_b64_e32 v[82:83], 0
	v_mov_b64_e32 v[72:73], 0
	v_mov_b64_e32 v[70:71], 0
	v_mov_b64_e32 v[68:69], 0
	v_mov_b64_e32 v[66:67], 0
	v_mov_b64_e32 v[64:65], 0
	v_mov_b64_e32 v[62:63], 0
	v_mov_b64_e32 v[60:61], 0
	v_mov_b64_e32 v[58:59], 0
	v_mov_b64_e32 v[48:49], 0
	v_mov_b64_e32 v[46:47], 0
	v_mov_b64_e32 v[44:45], 0
	v_mov_b64_e32 v[42:43], 0
	v_mov_b64_e32 v[32:33], 0
	v_mov_b64_e32 v[30:31], 0
	v_mov_b64_e32 v[28:29], 0
	v_mov_b64_e32 v[26:27], 0
	v_mov_b64_e32 v[16:17], 0
	v_mov_b64_e32 v[14:15], 0
	v_mov_b64_e32 v[12:13], 0
	v_mov_b64_e32 v[10:11], 0
	v_mov_b64_e32 v[56:57], 0
	v_mov_b64_e32 v[54:55], 0
	v_mov_b64_e32 v[52:53], 0
	v_mov_b64_e32 v[50:51], 0
	v_mov_b64_e32 v[40:41], 0
	v_mov_b64_e32 v[38:39], 0
	v_mov_b64_e32 v[36:37], 0
	v_mov_b64_e32 v[34:35], 0
	v_mov_b64_e32 v[24:25], 0
	v_mov_b64_e32 v[22:23], 0
	v_mov_b64_e32 v[20:21], 0
	v_mov_b64_e32 v[18:19], 0
	v_mov_b64_e32 v[8:9], 0
	v_mov_b64_e32 v[6:7], 0
	v_mov_b64_e32 v[4:5], 0
	v_mov_b64_e32 v[2:3], 0
	s_cbranch_vccnz .LBB0_1774
	s_add_u32 s28, s28, 0x80
	s_addc_u32 s29, s29, 0
	s_add_u32 s63, s38, 0x100
	v_mov_b32_e32 v2, 0
	s_addc_u32 s64, s39, 0
	s_mov_b32 s38, 0
	v_mov_b32_e32 v3, v2
	v_mov_b64_e32 v[4:5], 0
	v_mov_b64_e32 v[6:7], 0
	v_mov_b64_e32 v[8:9], 0
	v_mov_b64_e32 v[18:19], 0
	v_mov_b64_e32 v[20:21], 0
	v_mov_b64_e32 v[22:23], 0
	v_mov_b64_e32 v[24:25], 0
	v_mov_b64_e32 v[34:35], 0
	v_mov_b64_e32 v[36:37], 0
	v_mov_b64_e32 v[38:39], 0
	v_mov_b64_e32 v[40:41], 0
	v_mov_b64_e32 v[50:51], 0
	v_mov_b64_e32 v[52:53], 0
	v_mov_b64_e32 v[54:55], 0
	v_mov_b64_e32 v[56:57], 0
	v_mov_b64_e32 v[10:11], 0
	v_mov_b64_e32 v[12:13], 0
	v_mov_b64_e32 v[14:15], 0
	v_mov_b64_e32 v[16:17], 0
	v_mov_b64_e32 v[26:27], 0
	v_mov_b64_e32 v[28:29], 0
	v_mov_b64_e32 v[30:31], 0
	v_mov_b64_e32 v[32:33], 0
	v_mov_b64_e32 v[42:43], 0
	v_mov_b64_e32 v[44:45], 0
	v_mov_b64_e32 v[46:47], 0
	v_mov_b64_e32 v[48:49], 0
	v_mov_b64_e32 v[58:59], 0
	v_mov_b64_e32 v[60:61], 0
	v_mov_b64_e32 v[62:63], 0
	v_mov_b64_e32 v[64:65], 0
	v_mov_b64_e32 v[66:67], 0
	v_mov_b64_e32 v[68:69], 0
	v_mov_b64_e32 v[70:71], 0
	v_mov_b64_e32 v[72:73], 0
	v_mov_b64_e32 v[82:83], 0
	v_mov_b64_e32 v[84:85], 0
	v_mov_b64_e32 v[86:87], 0
	v_mov_b64_e32 v[88:89], 0
	v_mov_b64_e32 v[98:99], 0
	v_mov_b64_e32 v[100:101], 0
	v_mov_b64_e32 v[102:103], 0
	v_mov_b64_e32 v[104:105], 0
	v_mov_b64_e32 v[114:115], 0
	v_mov_b64_e32 v[116:117], 0
	v_mov_b64_e32 v[118:119], 0
	v_mov_b64_e32 v[120:121], 0
	v_mov_b64_e32 v[74:75], 0
	v_mov_b64_e32 v[76:77], 0
	v_mov_b64_e32 v[78:79], 0
	v_mov_b64_e32 v[80:81], 0
	v_mov_b64_e32 v[90:91], 0
	v_mov_b64_e32 v[92:93], 0
	v_mov_b64_e32 v[94:95], 0
	v_mov_b64_e32 v[96:97], 0
	v_mov_b64_e32 v[106:107], 0
	v_mov_b64_e32 v[108:109], 0
	v_mov_b64_e32 v[110:111], 0
	v_mov_b64_e32 v[112:113], 0
	v_mov_b64_e32 v[126:127], 0
	v_mov_b64_e32 v[128:129], 0
	v_mov_b64_e32 v[122:123], 0
	v_mov_b64_e32 v[124:125], 0
